# first grid barrier: the sixteen per-XCC census counter loads issued back to back and summed after one wait instead of fifteen serialized round trips
# speedup vs baseline: 1.0074x; 1.0074x over previous
.LBB0_2160:
	v_readlane_b32 s2, v252, 26
	v_readlane_b32 s3, v252, 27
	s_mov_b64 s[26:27], -1
	s_mov_b64 s[30:31], -1
	s_nop 2
	global_load_dword v0, v1, s[2:3] sc1
	v_readlane_b32 s2, v252, 28
	v_readlane_b32 s3, v252, 29
	s_waitcnt lgkmcnt(0)
	s_nop 3
	global_load_dword v2, v1, s[2:3] sc1
	v_readlane_b32 s2, v252, 30
	v_readlane_b32 s3, v252, 31
	s_nop 1
	s_nop 2
	global_load_dword v3, v1, s[2:3] sc1
	v_readlane_b32 s2, v252, 32
	v_readlane_b32 s3, v252, 33
	s_nop 1
	s_nop 2
	global_load_dword v4, v1, s[2:3] sc1
	v_readlane_b32 s2, v252, 34
	v_readlane_b32 s3, v252, 35
	s_nop 1
	s_nop 2
	global_load_dword v5, v1, s[2:3] sc1
	v_readlane_b32 s2, v252, 36
	v_readlane_b32 s3, v252, 37
	s_nop 1
	s_nop 2
	global_load_dword v6, v1, s[2:3] sc1
	v_readlane_b32 s2, v252, 38
	v_readlane_b32 s3, v252, 39
	s_nop 1
	s_nop 2
	global_load_dword v7, v1, s[2:3] sc1
	v_readlane_b32 s2, v252, 40
	v_readlane_b32 s3, v252, 41
	s_nop 1
	s_nop 2
	global_load_dword v8, v1, s[2:3] sc1
	v_readlane_b32 s2, v252, 42
	v_readlane_b32 s3, v252, 43
	s_nop 1
	s_nop 2
	global_load_dword v9, v1, s[2:3] sc1
	v_readlane_b32 s2, v252, 44
	v_readlane_b32 s3, v252, 45
	s_nop 1
	s_nop 2
	global_load_dword v10, v1, s[2:3] sc1
	v_readlane_b32 s2, v252, 46
	v_readlane_b32 s3, v252, 47
	s_nop 1
	s_nop 2
	global_load_dword v11, v1, s[2:3] sc1
	v_readlane_b32 s2, v252, 48
	v_readlane_b32 s3, v252, 49
	s_nop 1
	s_nop 2
	global_load_dword v12, v1, s[2:3] sc1
	v_readlane_b32 s2, v252, 50
	v_readlane_b32 s3, v252, 51
	s_nop 1
	s_nop 2
	global_load_dword v13, v1, s[2:3] sc1
	v_readlane_b32 s2, v252, 52
	v_readlane_b32 s3, v252, 53
	s_nop 1
	s_nop 2
	global_load_dword v14, v1, s[2:3] sc1
	v_readlane_b32 s2, v252, 54
	v_readlane_b32 s3, v252, 55
	s_nop 1
	s_nop 2
	global_load_dword v15, v1, s[2:3] sc1
	v_readlane_b32 s2, v252, 56
	v_readlane_b32 s3, v252, 57
	s_nop 1
	s_nop 2
	global_load_dword v16, v1, s[2:3] sc1
	v_readlane_b32 s2, v250, 0
	s_waitcnt vmcnt(0)
	v_add_u32_e32 v17, v2, v0
	v_add_u32_e32 v17, v17, v3
	v_add_u32_e32 v17, v17, v4
	v_add_u32_e32 v17, v17, v5
	v_add_u32_e32 v17, v17, v6
	v_add_u32_e32 v17, v17, v7
	v_add_u32_e32 v17, v17, v8
	v_add_u32_e32 v17, v17, v9
	v_add_u32_e32 v17, v17, v10
	v_add_u32_e32 v17, v17, v11
	v_add_u32_e32 v17, v17, v12
	v_add_u32_e32 v17, v17, v13
	v_add_u32_e32 v17, v17, v14
	v_add_u32_e32 v17, v17, v15
	v_add_u32_e32 v17, v17, v16
	v_cmp_eq_u32_e32 vcc, s2, v17
	s_cbranch_vccnz .LBB0_2159
	s_and_b32 s2, s33, 0xff
	s_cmp_eq_u32 s2, 0
	s_mov_b64 s[34:35], -1
	s_sleep 1
	s_cbranch_scc1 .LBB0_2164
	s_and_b64 vcc, exec, s[34:35]
	s_cbranch_vccz .LBB0_2159
